# v40 with s_sleep 1 -> s_sleep 0 in the 77 grid-barrier poll loops (shorter poll period)
# baseline (speedup 1.0000x reference)
.LBB0_63:
	s_sleep 0
	global_load_dword v2, v0, s[6:7] offset:32 sc1
	s_waitcnt vmcnt(0)
	v_and_b32_e32 v2, 0xffff0000, v2
	v_cmp_ne_u32_e32 vcc, v2, v1
	s_or_b64 s[8:9], vcc, s[8:9]
	s_andn2_b64 exec, exec, s[8:9]
	s_cbranch_execnz .LBB0_63

; __device__ __forceinline__ unsigned xb_ld(unsigned* p)              { return __hip_atomic_load(p, __ATOMIC_RELAXED, __HIP_MEMORY_SCOPE_AGENT); }
; __device__ __forceinline__ void xcd_barrier_complete(unsigned* bar, unsigned x, unsigned& nloc, unsigned& nx) {
;     ...
;     for (;;) {
;         sum = 0u; cnt = 0u; mine = 0u;
; #pragma unroll
;         for (unsigned j = 0; j < 16; ++j) { const unsigned c = xb_ld(&bar[XB_XCNT(j)]); sum += c; cnt += (c > 0u) ? 1u : 0u; mine = (j == x) ? c : mine; }
;         if (sum == G) break;
;         __builtin_amdgcn_s_sleep(1);
;         if ((++sp & 255u) == 0u) { if (xb_ld(&bar[XB_TMO])) break; if (sp > XB_SPIN_CAP) { atomicAdd(&bar[XB_TMO], 1u); break; } }
;     }
.LBB0_86:
	global_load_dword v12, v0, s[34:35] offset:1024 sc1
	s_waitcnt lgkmcnt(0)
	global_load_dword v1, v0, s[34:35] offset:1280 sc1
	global_load_dword v2, v0, s[34:35] offset:1536 sc1
	global_load_dword v3, v0, s[34:35] offset:1792 sc1
	global_load_dword v4, v0, s[34:35] offset:2048 sc1
	global_load_dword v5, v0, s[34:35] offset:2304 sc1
	global_load_dword v6, v0, s[34:35] offset:2560 sc1
	global_load_dword v7, v0, s[34:35] offset:2816 sc1
	global_load_dword v8, v0, s[34:35] offset:3072 sc1
	global_load_dword v9, v0, s[34:35] offset:3328 sc1
	global_load_dword v10, v0, s[34:35] offset:3584 sc1
	global_load_dword v11, v0, s[34:35] offset:3840 sc1
	v_readlane_b32 s0, v254, 60
	v_readlane_b32 s1, v254, 61
	s_nop 4
	global_load_dword v13, v0, s[0:1] sc1
	global_load_dword v14, v0, s[78:79] sc1
	global_load_dword v15, v0, s[80:81] sc1
	global_load_dword v16, v0, s[76:77] sc1
	s_mov_b64 s[12:13], -1
	s_mov_b64 s[14:15], -1
	s_waitcnt vmcnt(14)
	v_add_u32_e32 v17, v1, v12
	s_waitcnt vmcnt(13)
	v_add_u32_e32 v17, v17, v2
	s_waitcnt vmcnt(12)
	v_add_u32_e32 v17, v17, v3
	s_waitcnt vmcnt(11)
	v_add_u32_e32 v17, v17, v4
	s_waitcnt vmcnt(10)
	v_add_u32_e32 v17, v17, v5
	s_waitcnt vmcnt(9)
	v_add_u32_e32 v17, v17, v6
	s_waitcnt vmcnt(8)
	v_add_u32_e32 v17, v17, v7
	s_waitcnt vmcnt(7)
	v_add_u32_e32 v17, v17, v8
	s_waitcnt vmcnt(6)
	v_add_u32_e32 v17, v17, v9
	s_waitcnt vmcnt(5)
	v_add_u32_e32 v17, v17, v10
	s_waitcnt vmcnt(4)
	v_add_u32_e32 v17, v17, v11
	s_waitcnt vmcnt(3)
	v_add_u32_e32 v17, v17, v13
	s_waitcnt vmcnt(2)
	v_add_u32_e32 v17, v17, v14
	s_waitcnt vmcnt(1)
	v_add_u32_e32 v17, v17, v15
	s_waitcnt vmcnt(0)
	v_add_u32_e32 v17, v17, v16
	v_cmp_eq_u32_e32 vcc, s36, v17
	s_cbranch_vccnz .LBB0_85
	s_and_b32 s0, s5, 0xff
	s_cmp_eq_u32 s0, 0
	s_mov_b64 s[40:41], -1
	s_sleep 0
	s_cbranch_scc0 .LBB0_90
	global_load_dword v17, v0, s[74:75] sc1
	s_waitcnt vmcnt(0)
	v_cmp_eq_u32_e32 vcc, 0, v17
	s_cbranch_vccnz .LBB0_92
	s_mov_b64 s[40:41], 0

.LBB0_105:
	s_and_b32 s0, s5, 0xff
	s_mov_b64 s[46:47], -1
	s_cmp_lg_u32 s0, 0
	s_mov_b64 s[50:51], -1
	s_sleep 0
	s_cbranch_scc1 .LBB0_108
	global_load_dword v1, v0, s[74:75] sc1
	s_waitcnt vmcnt(0)
	v_cmp_eq_u32_e32 vcc, 0, v1
	s_cbranch_vccnz .LBB0_110
	s_mov_b64 s[50:51], 0
	s_mov_b64 s[48:49], -1

.LBB0_144:
	s_sleep 0
	global_load_dword v2, v0, s[12:13] offset:32 sc1
	s_waitcnt vmcnt(0)
	v_and_b32_e32 v2, 0xffff0000, v2
	v_cmp_ne_u32_e32 vcc, v2, v1
	s_or_b64 s[14:15], vcc, s[14:15]
	s_andn2_b64 exec, exec, s[14:15]
	s_cbranch_execnz .LBB0_144

; __device__ __forceinline__ unsigned xb_ld(unsigned* p)              { return __hip_atomic_load(p, __ATOMIC_RELAXED, __HIP_MEMORY_SCOPE_AGENT); }
; __device__ __forceinline__ void xcd_barrier_complete(unsigned* bar, unsigned x, unsigned& nloc, unsigned& nx) {
;     ...
;     for (;;) {
;         sum = 0u; cnt = 0u; mine = 0u;
; #pragma unroll
;         for (unsigned j = 0; j < 16; ++j) { const unsigned c = xb_ld(&bar[XB_XCNT(j)]); sum += c; cnt += (c > 0u) ? 1u : 0u; mine = (j == x) ? c : mine; }
;         if (sum == G) break;
;         __builtin_amdgcn_s_sleep(1);
;         if ((++sp & 255u) == 0u) { if (xb_ld(&bar[XB_TMO])) break; if (sp > XB_SPIN_CAP) { atomicAdd(&bar[XB_TMO], 1u); break; } }
;     }
.LBB0_175:
	global_load_dword v12, v0, s[34:35] offset:1024 sc1
	global_load_dword v1, v0, s[34:35] offset:1280 sc1
	s_waitcnt lgkmcnt(0)
	global_load_dword v2, v0, s[34:35] offset:1536 sc1
	global_load_dword v3, v0, s[34:35] offset:1792 sc1
	global_load_dword v4, v0, s[34:35] offset:2048 sc1
	global_load_dword v5, v0, s[34:35] offset:2304 sc1
	global_load_dword v6, v0, s[34:35] offset:2560 sc1
	global_load_dword v7, v0, s[34:35] offset:2816 sc1
	global_load_dword v8, v0, s[34:35] offset:3072 sc1
	global_load_dword v9, v0, s[34:35] offset:3328 sc1
	global_load_dword v10, v0, s[34:35] offset:3584 sc1
	global_load_dword v11, v0, s[34:35] offset:3840 sc1
	v_readlane_b32 s0, v254, 60
	v_readlane_b32 s1, v254, 61
	s_nop 4
	global_load_dword v13, v0, s[0:1] sc1
	global_load_dword v14, v0, s[78:79] sc1
	global_load_dword v15, v0, s[80:81] sc1
	global_load_dword v16, v0, s[76:77] sc1
	s_mov_b64 s[12:13], -1
	s_mov_b64 s[14:15], -1
	s_waitcnt vmcnt(14)
	v_add_u32_e32 v17, v1, v12
	s_waitcnt vmcnt(13)
	v_add_u32_e32 v17, v17, v2
	s_waitcnt vmcnt(12)
	v_add_u32_e32 v17, v17, v3
	s_waitcnt vmcnt(11)
	v_add_u32_e32 v17, v17, v4
	s_waitcnt vmcnt(10)
	v_add_u32_e32 v17, v17, v5
	s_waitcnt vmcnt(9)
	v_add_u32_e32 v17, v17, v6
	s_waitcnt vmcnt(8)
	v_add_u32_e32 v17, v17, v7
	s_waitcnt vmcnt(7)
	v_add_u32_e32 v17, v17, v8
	s_waitcnt vmcnt(6)
	v_add_u32_e32 v17, v17, v9
	s_waitcnt vmcnt(5)
	v_add_u32_e32 v17, v17, v10
	s_waitcnt vmcnt(4)
	v_add_u32_e32 v17, v17, v11
	s_waitcnt vmcnt(3)
	v_add_u32_e32 v17, v17, v13
	s_waitcnt vmcnt(2)
	v_add_u32_e32 v17, v17, v14
	s_waitcnt vmcnt(1)
	v_add_u32_e32 v17, v17, v15
	s_waitcnt vmcnt(0)
	v_add_u32_e32 v17, v17, v16
	v_cmp_eq_u32_e32 vcc, s36, v17
	s_cbranch_vccnz .LBB0_174
	s_and_b32 s0, s4, 0xff
	s_cmp_eq_u32 s0, 0
	s_mov_b64 s[40:41], -1
	s_sleep 0
	s_cbranch_scc0 .LBB0_179
	global_load_dword v17, v0, s[74:75] sc1
	s_waitcnt vmcnt(0)
	v_cmp_eq_u32_e32 vcc, 0, v17
	s_cbranch_vccnz .LBB0_181
	s_mov_b64 s[40:41], 0

.LBB0_194:
	s_and_b32 s0, s4, 0xff
	s_mov_b64 s[46:47], -1
	s_cmp_lg_u32 s0, 0
	s_mov_b64 s[52:53], -1
	s_sleep 0
	s_cbranch_scc1 .LBB0_197
	global_load_dword v2, v0, s[74:75] sc1
	s_waitcnt vmcnt(0)
	v_cmp_eq_u32_e32 vcc, 0, v2
	s_cbranch_vccnz .LBB0_199
	s_mov_b64 s[52:53], 0
	s_mov_b64 s[50:51], -1

.LBB0_519:
	s_and_b32 s0, s4, 0xff
	s_mov_b64 s[46:47], -1
	s_cmp_lg_u32 s0, 0
	s_mov_b64 s[50:51], -1
	s_sleep 0
	s_cbranch_scc1 .LBB0_522
	global_load_dword v2, v0, s[74:75] sc1
	s_waitcnt vmcnt(0)
	v_cmp_eq_u32_e32 vcc, 0, v2
	s_cbranch_vccnz .LBB0_524
	s_mov_b64 s[50:51], 0
	s_mov_b64 s[48:49], -1

; __device__ __forceinline__ unsigned xb_ld(unsigned* p)              { return __hip_atomic_load(p, __ATOMIC_RELAXED, __HIP_MEMORY_SCOPE_AGENT); }
; __device__ __forceinline__ void xcd_barrier_complete(unsigned* bar, unsigned x, unsigned& nloc, unsigned& nx) {
;     ...
;     for (;;) {
;         sum = 0u; cnt = 0u; mine = 0u;
; #pragma unroll
;         for (unsigned j = 0; j < 16; ++j) { const unsigned c = xb_ld(&bar[XB_XCNT(j)]); sum += c; cnt += (c > 0u) ? 1u : 0u; mine = (j == x) ? c : mine; }
;         if (sum == G) break;
;         __builtin_amdgcn_s_sleep(1);
;         if ((++sp & 255u) == 0u) { if (xb_ld(&bar[XB_TMO])) break; if (sp > XB_SPIN_CAP) { atomicAdd(&bar[XB_TMO], 1u); break; } }
;     }
.LBB0_614:
	global_load_dword v12, v0, s[34:35] offset:1024 sc1
	global_load_dword v1, v0, s[34:35] offset:1280 sc1
	s_waitcnt lgkmcnt(0)
	global_load_dword v2, v0, s[34:35] offset:1536 sc1
	global_load_dword v3, v0, s[34:35] offset:1792 sc1
	global_load_dword v4, v0, s[34:35] offset:2048 sc1
	global_load_dword v5, v0, s[34:35] offset:2304 sc1
	global_load_dword v6, v0, s[34:35] offset:2560 sc1
	global_load_dword v7, v0, s[34:35] offset:2816 sc1
	global_load_dword v8, v0, s[34:35] offset:3072 sc1
	global_load_dword v9, v0, s[34:35] offset:3328 sc1
	global_load_dword v10, v0, s[34:35] offset:3584 sc1
	global_load_dword v11, v0, s[34:35] offset:3840 sc1
	v_readlane_b32 s0, v254, 60
	v_readlane_b32 s1, v254, 61
	s_nop 4
	global_load_dword v13, v0, s[0:1] sc1
	global_load_dword v14, v0, s[78:79] sc1
	global_load_dword v15, v0, s[80:81] sc1
	global_load_dword v16, v0, s[76:77] sc1
	s_mov_b64 s[12:13], -1
	s_mov_b64 s[14:15], -1
	s_waitcnt vmcnt(14)
	v_add_u32_e32 v17, v1, v12
	s_waitcnt vmcnt(13)
	v_add_u32_e32 v17, v17, v2
	s_waitcnt vmcnt(12)
	v_add_u32_e32 v17, v17, v3
	s_waitcnt vmcnt(11)
	v_add_u32_e32 v17, v17, v4
	s_waitcnt vmcnt(10)
	v_add_u32_e32 v17, v17, v5
	s_waitcnt vmcnt(9)
	v_add_u32_e32 v17, v17, v6
	s_waitcnt vmcnt(8)
	v_add_u32_e32 v17, v17, v7
	s_waitcnt vmcnt(7)
	v_add_u32_e32 v17, v17, v8
	s_waitcnt vmcnt(6)
	v_add_u32_e32 v17, v17, v9
	s_waitcnt vmcnt(5)
	v_add_u32_e32 v17, v17, v10
	s_waitcnt vmcnt(4)
	v_add_u32_e32 v17, v17, v11
	s_waitcnt vmcnt(3)
	v_add_u32_e32 v17, v17, v13
	s_waitcnt vmcnt(2)
	v_add_u32_e32 v17, v17, v14
	s_waitcnt vmcnt(1)
	v_add_u32_e32 v17, v17, v15
	s_waitcnt vmcnt(0)
	v_add_u32_e32 v17, v17, v16
	v_cmp_eq_u32_e32 vcc, s36, v17
	s_cbranch_vccnz .LBB0_613
	s_and_b32 s0, s7, 0xff
	s_cmp_eq_u32 s0, 0
	s_mov_b64 s[40:41], -1
	s_sleep 0
	s_cbranch_scc0 .LBB0_618
	global_load_dword v17, v0, s[74:75] sc1
	s_waitcnt vmcnt(0)
	v_cmp_eq_u32_e32 vcc, 0, v17
	s_cbranch_vccnz .LBB0_620
	s_mov_b64 s[40:41], 0

.LBB0_634:
	s_and_b32 s0, s7, 0xff
	s_mov_b64 s[46:47], -1
	s_cmp_lg_u32 s0, 0
	s_mov_b64 s[50:51], -1
	s_sleep 0
	s_cbranch_scc1 .LBB0_637
	global_load_dword v2, v0, s[74:75] sc1
	s_waitcnt vmcnt(0)
	v_cmp_eq_u32_e32 vcc, 0, v2
	s_cbranch_vccnz .LBB0_639
	s_mov_b64 s[50:51], 0
	s_mov_b64 s[48:49], -1

.LBB0_746:
	s_sleep 0
	global_load_dword v2, v0, s[12:13] offset:32 sc1
	s_waitcnt vmcnt(0)
	v_and_b32_e32 v2, 0xffff0000, v2
	v_cmp_ne_u32_e32 vcc, v2, v1
	s_or_b64 s[14:15], vcc, s[14:15]
	s_andn2_b64 exec, exec, s[14:15]
	s_cbranch_execnz .LBB0_746
	s_branch .LBB0_468

.LBB0_852:
	s_and_b32 s0, s4, 0xff
	s_mov_b64 s[46:47], -1
	s_cmp_lg_u32 s0, 0
	s_mov_b64 s[62:63], -1
	s_sleep 0
	s_cbranch_scc1 .LBB0_855
	global_load_dword v2, v0, s[74:75] sc1
	s_waitcnt vmcnt(0)
	v_cmp_eq_u32_e32 vcc, 0, v2
	s_cbranch_vccnz .LBB0_857
	s_mov_b64 s[62:63], 0
	s_mov_b64 s[60:61], -1

; __device__ __forceinline__ unsigned xb_ld(unsigned* p)              { return __hip_atomic_load(p, __ATOMIC_RELAXED, __HIP_MEMORY_SCOPE_AGENT); }
; __device__ __forceinline__ void xcd_barrier_complete(unsigned* bar, unsigned x, unsigned& nloc, unsigned& nx) {
;     ...
;     for (;;) {
;         sum = 0u; cnt = 0u; mine = 0u;
; #pragma unroll
;         for (unsigned j = 0; j < 16; ++j) { const unsigned c = xb_ld(&bar[XB_XCNT(j)]); sum += c; cnt += (c > 0u) ? 1u : 0u; mine = (j == x) ? c : mine; }
;         if (sum == G) break;
;         __builtin_amdgcn_s_sleep(1);
;         if ((++sp & 255u) == 0u) { if (xb_ld(&bar[XB_TMO])) break; if (sp > XB_SPIN_CAP) { atomicAdd(&bar[XB_TMO], 1u); break; } }
;     }
.LBB0_1062:
	global_load_dword v12, v0, s[34:35] offset:1024 sc1
	global_load_dword v1, v0, s[34:35] offset:1280 sc1
	s_waitcnt lgkmcnt(0)
	global_load_dword v2, v0, s[34:35] offset:1536 sc1
	global_load_dword v3, v0, s[34:35] offset:1792 sc1
	global_load_dword v4, v0, s[34:35] offset:2048 sc1
	global_load_dword v5, v0, s[34:35] offset:2304 sc1
	global_load_dword v6, v0, s[34:35] offset:2560 sc1
	global_load_dword v7, v0, s[34:35] offset:2816 sc1
	global_load_dword v8, v0, s[34:35] offset:3072 sc1
	global_load_dword v9, v0, s[34:35] offset:3328 sc1
	global_load_dword v10, v0, s[34:35] offset:3584 sc1
	global_load_dword v11, v0, s[34:35] offset:3840 sc1
	v_readlane_b32 s0, v254, 60
	v_readlane_b32 s1, v254, 61
	s_nop 4
	global_load_dword v13, v0, s[0:1] sc1
	global_load_dword v14, v0, s[78:79] sc1
	global_load_dword v15, v0, s[80:81] sc1
	global_load_dword v16, v0, s[76:77] sc1
	s_mov_b64 s[12:13], -1
	s_mov_b64 s[14:15], -1
	s_waitcnt vmcnt(14)
	v_add_u32_e32 v17, v1, v12
	s_waitcnt vmcnt(13)
	v_add_u32_e32 v17, v17, v2
	s_waitcnt vmcnt(12)
	v_add_u32_e32 v17, v17, v3
	s_waitcnt vmcnt(11)
	v_add_u32_e32 v17, v17, v4
	s_waitcnt vmcnt(10)
	v_add_u32_e32 v17, v17, v5
	s_waitcnt vmcnt(9)
	v_add_u32_e32 v17, v17, v6
	s_waitcnt vmcnt(8)
	v_add_u32_e32 v17, v17, v7
	s_waitcnt vmcnt(7)
	v_add_u32_e32 v17, v17, v8
	s_waitcnt vmcnt(6)
	v_add_u32_e32 v17, v17, v9
	s_waitcnt vmcnt(5)
	v_add_u32_e32 v17, v17, v10
	s_waitcnt vmcnt(4)
	v_add_u32_e32 v17, v17, v11
	s_waitcnt vmcnt(3)
	v_add_u32_e32 v17, v17, v13
	s_waitcnt vmcnt(2)
	v_add_u32_e32 v17, v17, v14
	s_waitcnt vmcnt(1)
	v_add_u32_e32 v17, v17, v15
	s_waitcnt vmcnt(0)
	v_add_u32_e32 v17, v17, v16
	v_cmp_eq_u32_e32 vcc, s36, v17
	s_cbranch_vccnz .LBB0_1061
	s_and_b32 s0, s5, 0xff
	s_cmp_eq_u32 s0, 0
	s_mov_b64 s[40:41], -1
	s_sleep 0
	s_cbranch_scc0 .LBB0_1066
	v_readlane_b32 s0, v255, 22
	v_readlane_b32 s1, v255, 23
	s_nop 4
	global_load_dword v17, v0, s[0:1] sc1
	s_waitcnt vmcnt(0)
	v_cmp_eq_u32_e32 vcc, 0, v17
	s_cbranch_vccnz .LBB0_1068
	s_mov_b64 s[40:41], 0

.LBB0_1081:
	s_and_b32 s0, s5, 0xff
	s_mov_b64 s[46:47], -1
	s_cmp_lg_u32 s0, 0
	s_mov_b64 s[54:55], -1
	s_sleep 0
	s_cbranch_scc1 .LBB0_1084
	v_readlane_b32 s0, v255, 22
	v_readlane_b32 s1, v255, 23
	s_nop 4
	global_load_dword v2, v0, s[0:1] sc1
	s_waitcnt vmcnt(0)
	v_cmp_eq_u32_e32 vcc, 0, v2
	s_cbranch_vccnz .LBB0_1086
	s_mov_b64 s[54:55], 0
	s_mov_b64 s[48:49], -1

.LBB0_1115:
	s_and_b32 s0, s4, 0xff
	s_mov_b64 s[46:47], -1
	s_cmp_lg_u32 s0, 0
	s_mov_b64 s[56:57], -1
	s_sleep 0
	s_cbranch_scc1 .LBB0_1118
	global_load_dword v2, v0, s[74:75] sc1
	s_waitcnt vmcnt(0)
	v_cmp_eq_u32_e32 vcc, 0, v2
	s_cbranch_vccnz .LBB0_1120
	s_mov_b64 s[56:57], 0
	s_mov_b64 s[54:55], -1

; __device__ __forceinline__ unsigned xb_ld(unsigned* p)              { return __hip_atomic_load(p, __ATOMIC_RELAXED, __HIP_MEMORY_SCOPE_AGENT); }
; __device__ __forceinline__ void xcd_barrier_complete(unsigned* bar, unsigned x, unsigned& nloc, unsigned& nx) {
;     ...
;     for (;;) {
;         sum = 0u; cnt = 0u; mine = 0u;
; #pragma unroll
;         for (unsigned j = 0; j < 16; ++j) { const unsigned c = xb_ld(&bar[XB_XCNT(j)]); sum += c; cnt += (c > 0u) ? 1u : 0u; mine = (j == x) ? c : mine; }
;         if (sum == G) break;
;         __builtin_amdgcn_s_sleep(1);
;         if ((++sp & 255u) == 0u) { if (xb_ld(&bar[XB_TMO])) break; if (sp > XB_SPIN_CAP) { atomicAdd(&bar[XB_TMO], 1u); break; } }
;     }
.LBB0_1152:
	global_load_dword v12, v0, s[34:35] offset:1024 sc1
	global_load_dword v1, v0, s[34:35] offset:1280 sc1
	s_waitcnt lgkmcnt(0)
	global_load_dword v2, v0, s[34:35] offset:1536 sc1
	global_load_dword v3, v0, s[34:35] offset:1792 sc1
	global_load_dword v4, v0, s[34:35] offset:2048 sc1
	global_load_dword v5, v0, s[34:35] offset:2304 sc1
	global_load_dword v6, v0, s[34:35] offset:2560 sc1
	global_load_dword v7, v0, s[34:35] offset:2816 sc1
	global_load_dword v8, v0, s[34:35] offset:3072 sc1
	global_load_dword v9, v0, s[34:35] offset:3328 sc1
	global_load_dword v10, v0, s[34:35] offset:3584 sc1
	global_load_dword v11, v0, s[34:35] offset:3840 sc1
	v_readlane_b32 s0, v254, 60
	v_readlane_b32 s1, v254, 61
	s_nop 4
	global_load_dword v13, v0, s[0:1] sc1
	global_load_dword v14, v0, s[78:79] sc1
	global_load_dword v15, v0, s[80:81] sc1
	global_load_dword v16, v0, s[76:77] sc1
	s_mov_b64 s[12:13], -1
	s_mov_b64 s[14:15], -1
	s_waitcnt vmcnt(14)
	v_add_u32_e32 v17, v1, v12
	s_waitcnt vmcnt(13)
	v_add_u32_e32 v17, v17, v2
	s_waitcnt vmcnt(12)
	v_add_u32_e32 v17, v17, v3
	s_waitcnt vmcnt(11)
	v_add_u32_e32 v17, v17, v4
	s_waitcnt vmcnt(10)
	v_add_u32_e32 v17, v17, v5
	s_waitcnt vmcnt(9)
	v_add_u32_e32 v17, v17, v6
	s_waitcnt vmcnt(8)
	v_add_u32_e32 v17, v17, v7
	s_waitcnt vmcnt(7)
	v_add_u32_e32 v17, v17, v8
	s_waitcnt vmcnt(6)
	v_add_u32_e32 v17, v17, v9
	s_waitcnt vmcnt(5)
	v_add_u32_e32 v17, v17, v10
	s_waitcnt vmcnt(4)
	v_add_u32_e32 v17, v17, v11
	s_waitcnt vmcnt(3)
	v_add_u32_e32 v17, v17, v13
	s_waitcnt vmcnt(2)
	v_add_u32_e32 v17, v17, v14
	s_waitcnt vmcnt(1)
	v_add_u32_e32 v17, v17, v15
	s_waitcnt vmcnt(0)
	v_add_u32_e32 v17, v17, v16
	v_cmp_eq_u32_e32 vcc, s36, v17
	s_cbranch_vccnz .LBB0_1151
	s_and_b32 s0, s4, 0xff
	s_cmp_eq_u32 s0, 0
	s_mov_b64 s[40:41], -1
	s_sleep 0
	s_cbranch_scc0 .LBB0_1156
	v_readlane_b32 s0, v255, 22
	v_readlane_b32 s1, v255, 23
	s_nop 4
	global_load_dword v17, v0, s[0:1] sc1
	s_waitcnt vmcnt(0)
	v_cmp_eq_u32_e32 vcc, 0, v17
	s_cbranch_vccnz .LBB0_1158
	s_mov_b64 s[40:41], 0

.LBB0_1171:
	s_and_b32 s0, s4, 0xff
	s_mov_b64 s[46:47], -1
	s_cmp_lg_u32 s0, 0
	s_mov_b64 s[50:51], -1
	s_sleep 0
	s_cbranch_scc1 .LBB0_1174
	v_readlane_b32 s0, v255, 22
	v_readlane_b32 s1, v255, 23
	s_nop 4
	global_load_dword v2, v0, s[0:1] sc1
	s_waitcnt vmcnt(0)
	v_cmp_eq_u32_e32 vcc, 0, v2
	s_cbranch_vccnz .LBB0_1176
	s_mov_b64 s[50:51], 0
	s_mov_b64 s[48:49], -1

.LBB0_1275:
	s_and_b32 s0, s4, 0xff
	s_mov_b64 s[46:47], -1
	s_cmp_lg_u32 s0, 0
	s_mov_b64 s[58:59], -1
	s_sleep 0
	s_cbranch_scc1 .LBB0_1278
	global_load_dword v2, v0, s[74:75] sc1
	s_waitcnt vmcnt(0)
	v_cmp_eq_u32_e32 vcc, 0, v2
	s_cbranch_vccnz .LBB0_1280
	s_mov_b64 s[58:59], 0
	s_mov_b64 s[48:49], -1

.LBB0_1351:
	s_and_b32 s0, s4, 0xff
	s_mov_b64 s[48:49], -1
	s_cmp_lg_u32 s0, 0
	s_mov_b64 s[60:61], -1
	s_sleep 0
	s_cbranch_scc1 .LBB0_1354
	v_readlane_b32 s0, v255, 22
	v_readlane_b32 s1, v255, 23
	s_nop 4
	global_load_dword v2, v0, s[0:1] sc1
	s_waitcnt vmcnt(0)
	v_cmp_eq_u32_e32 vcc, 0, v2
	s_cbranch_vccnz .LBB0_1356
	s_mov_b64 s[60:61], 0
	s_mov_b64 s[58:59], -1

; __device__ __forceinline__ unsigned xb_ld(unsigned* p)              { return __hip_atomic_load(p, __ATOMIC_RELAXED, __HIP_MEMORY_SCOPE_AGENT); }
; __device__ __forceinline__ void xcd_barrier_complete(unsigned* bar, unsigned x, unsigned& nloc, unsigned& nx) {
;     ...
;     for (;;) {
;         sum = 0u; cnt = 0u; mine = 0u;
; #pragma unroll
;         for (unsigned j = 0; j < 16; ++j) { const unsigned c = xb_ld(&bar[XB_XCNT(j)]); sum += c; cnt += (c > 0u) ? 1u : 0u; mine = (j == x) ? c : mine; }
;         if (sum == G) break;
;         __builtin_amdgcn_s_sleep(1);
;         if ((++sp & 255u) == 0u) { if (xb_ld(&bar[XB_TMO])) break; if (sp > XB_SPIN_CAP) { atomicAdd(&bar[XB_TMO], 1u); break; } }
;     }
.LBB0_1417:
	global_load_dword v12, v0, s[34:35] offset:1024 sc1
	global_load_dword v1, v0, s[34:35] offset:1280 sc1
	s_waitcnt lgkmcnt(0)
	global_load_dword v2, v0, s[34:35] offset:1536 sc1
	global_load_dword v3, v0, s[34:35] offset:1792 sc1
	global_load_dword v4, v0, s[34:35] offset:2048 sc1
	global_load_dword v5, v0, s[34:35] offset:2304 sc1
	global_load_dword v6, v0, s[34:35] offset:2560 sc1
	global_load_dword v7, v0, s[34:35] offset:2816 sc1
	global_load_dword v8, v0, s[34:35] offset:3072 sc1
	global_load_dword v9, v0, s[34:35] offset:3328 sc1
	global_load_dword v10, v0, s[34:35] offset:3584 sc1
	global_load_dword v11, v0, s[34:35] offset:3840 sc1
	v_readlane_b32 s0, v254, 60
	v_readlane_b32 s1, v254, 61
	s_nop 4
	global_load_dword v13, v0, s[0:1] sc1
	global_load_dword v14, v0, s[78:79] sc1
	global_load_dword v15, v0, s[80:81] sc1
	global_load_dword v16, v0, s[76:77] sc1
	s_mov_b64 s[12:13], -1
	s_mov_b64 s[14:15], -1
	s_waitcnt vmcnt(14)
	v_add_u32_e32 v17, v1, v12
	s_waitcnt vmcnt(13)
	v_add_u32_e32 v17, v17, v2
	s_waitcnt vmcnt(12)
	v_add_u32_e32 v17, v17, v3
	s_waitcnt vmcnt(11)
	v_add_u32_e32 v17, v17, v4
	s_waitcnt vmcnt(10)
	v_add_u32_e32 v17, v17, v5
	s_waitcnt vmcnt(9)
	v_add_u32_e32 v17, v17, v6
	s_waitcnt vmcnt(8)
	v_add_u32_e32 v17, v17, v7
	s_waitcnt vmcnt(7)
	v_add_u32_e32 v17, v17, v8
	s_waitcnt vmcnt(6)
	v_add_u32_e32 v17, v17, v9
	s_waitcnt vmcnt(5)
	v_add_u32_e32 v17, v17, v10
	s_waitcnt vmcnt(4)
	v_add_u32_e32 v17, v17, v11
	s_waitcnt vmcnt(3)
	v_add_u32_e32 v17, v17, v13
	s_waitcnt vmcnt(2)
	v_add_u32_e32 v17, v17, v14
	s_waitcnt vmcnt(1)
	v_add_u32_e32 v17, v17, v15
	s_waitcnt vmcnt(0)
	v_add_u32_e32 v17, v17, v16
	v_cmp_eq_u32_e32 vcc, s36, v17
	s_cbranch_vccnz .LBB0_1416
	s_and_b32 s0, s5, 0xff
	s_cmp_eq_u32 s0, 0
	s_mov_b64 s[40:41], -1
	s_sleep 0
	s_cbranch_scc0 .LBB0_1421
	global_load_dword v17, v0, s[58:59] sc1
	s_waitcnt vmcnt(0)
	v_cmp_eq_u32_e32 vcc, 0, v17
	s_cbranch_vccnz .LBB0_1423
	s_mov_b64 s[40:41], 0

.LBB0_1436:
	s_and_b32 s0, s5, 0xff
	s_mov_b64 s[46:47], -1
	s_cmp_lg_u32 s0, 0
	s_mov_b64 s[52:53], -1
	s_sleep 0
	s_cbranch_scc1 .LBB0_1439
	global_load_dword v2, v0, s[58:59] sc1
	s_waitcnt vmcnt(0)
	v_cmp_eq_u32_e32 vcc, 0, v2
	s_cbranch_vccnz .LBB0_1441
	s_mov_b64 s[52:53], 0
	s_mov_b64 s[48:49], -1

.LBB0_1511:
	s_and_b32 s0, s4, 0xff
	s_mov_b64 s[46:47], -1
	s_cmp_lg_u32 s0, 0
	s_mov_b64 s[52:53], -1
	s_sleep 0
	s_cbranch_scc1 .LBB0_1514
	v_readlane_b32 s0, v255, 22
	v_readlane_b32 s1, v255, 23
	s_nop 4
	global_load_dword v2, v0, s[0:1] sc1
	s_waitcnt vmcnt(0)
	v_cmp_eq_u32_e32 vcc, 0, v2
	s_cbranch_vccnz .LBB0_1516
	s_mov_b64 s[52:53], 0
	s_mov_b64 s[48:49], -1

.LBB0_1756:
	s_and_b32 s0, s4, 0xff
	s_mov_b64 s[52:53], -1
	s_cmp_lg_u32 s0, 0
	s_mov_b64 s[56:57], -1
	s_sleep 0
	s_cbranch_scc1 .LBB0_1759
	v_readlane_b32 s0, v255, 22
	v_readlane_b32 s1, v255, 23
	s_nop 4
	global_load_dword v2, v0, s[0:1] sc1
	s_waitcnt vmcnt(0)
	v_cmp_eq_u32_e32 vcc, 0, v2
	s_cbranch_vccnz .LBB0_1761
	s_mov_b64 s[56:57], 0
	s_mov_b64 s[54:55], -1

; __device__ __forceinline__ unsigned xb_ld(unsigned* p)              { return __hip_atomic_load(p, __ATOMIC_RELAXED, __HIP_MEMORY_SCOPE_AGENT); }
; __device__ __forceinline__ void xcd_barrier_complete(unsigned* bar, unsigned x, unsigned& nloc, unsigned& nx) {
;     ...
;     for (;;) {
;         sum = 0u; cnt = 0u; mine = 0u;
; #pragma unroll
;         for (unsigned j = 0; j < 16; ++j) { const unsigned c = xb_ld(&bar[XB_XCNT(j)]); sum += c; cnt += (c > 0u) ? 1u : 0u; mine = (j == x) ? c : mine; }
;         if (sum == G) break;
;         __builtin_amdgcn_s_sleep(1);
;         if ((++sp & 255u) == 0u) { if (xb_ld(&bar[XB_TMO])) break; if (sp > XB_SPIN_CAP) { atomicAdd(&bar[XB_TMO], 1u); break; } }
;     }
.LBB0_1841:
	global_load_dword v12, v0, s[34:35] offset:1024 sc1
	global_load_dword v1, v0, s[34:35] offset:1280 sc1
	s_waitcnt lgkmcnt(0)
	global_load_dword v2, v0, s[34:35] offset:1536 sc1
	global_load_dword v3, v0, s[34:35] offset:1792 sc1
	global_load_dword v4, v0, s[34:35] offset:2048 sc1
	global_load_dword v5, v0, s[34:35] offset:2304 sc1
	global_load_dword v6, v0, s[34:35] offset:2560 sc1
	global_load_dword v7, v0, s[34:35] offset:2816 sc1
	global_load_dword v8, v0, s[34:35] offset:3072 sc1
	global_load_dword v9, v0, s[34:35] offset:3328 sc1
	global_load_dword v10, v0, s[34:35] offset:3584 sc1
	global_load_dword v11, v0, s[34:35] offset:3840 sc1
	v_readlane_b32 s0, v254, 60
	v_readlane_b32 s1, v254, 61
	s_nop 4
	global_load_dword v13, v0, s[0:1] sc1
	global_load_dword v14, v0, s[78:79] sc1
	global_load_dword v15, v0, s[80:81] sc1
	global_load_dword v16, v0, s[76:77] sc1
	s_mov_b64 s[12:13], -1
	s_mov_b64 s[14:15], -1
	s_waitcnt vmcnt(14)
	v_add_u32_e32 v17, v1, v12
	s_waitcnt vmcnt(13)
	v_add_u32_e32 v17, v17, v2
	s_waitcnt vmcnt(12)
	v_add_u32_e32 v17, v17, v3
	s_waitcnt vmcnt(11)
	v_add_u32_e32 v17, v17, v4
	s_waitcnt vmcnt(10)
	v_add_u32_e32 v17, v17, v5
	s_waitcnt vmcnt(9)
	v_add_u32_e32 v17, v17, v6
	s_waitcnt vmcnt(8)
	v_add_u32_e32 v17, v17, v7
	s_waitcnt vmcnt(7)
	v_add_u32_e32 v17, v17, v8
	s_waitcnt vmcnt(6)
	v_add_u32_e32 v17, v17, v9
	s_waitcnt vmcnt(5)
	v_add_u32_e32 v17, v17, v10
	s_waitcnt vmcnt(4)
	v_add_u32_e32 v17, v17, v11
	s_waitcnt vmcnt(3)
	v_add_u32_e32 v17, v17, v13
	s_waitcnt vmcnt(2)
	v_add_u32_e32 v17, v17, v14
	s_waitcnt vmcnt(1)
	v_add_u32_e32 v17, v17, v15
	s_waitcnt vmcnt(0)
	v_add_u32_e32 v17, v17, v16
	v_cmp_eq_u32_e32 vcc, s36, v17
	s_cbranch_vccnz .LBB0_1840
	s_and_b32 s0, s7, 0xff
	s_cmp_eq_u32 s0, 0
	s_mov_b64 s[40:41], -1
	s_sleep 0
	s_cbranch_scc0 .LBB0_1845
	v_readlane_b32 s0, v255, 22
	v_readlane_b32 s1, v255, 23
	s_nop 4
	global_load_dword v17, v0, s[0:1] sc1
	s_waitcnt vmcnt(0)
	v_cmp_eq_u32_e32 vcc, 0, v17
	s_cbranch_vccnz .LBB0_1847
	s_mov_b64 s[40:41], 0

.LBB0_1860:
	s_and_b32 s0, s7, 0xff
	s_mov_b64 s[48:49], -1
	s_cmp_lg_u32 s0, 0
	s_mov_b64 s[52:53], -1
	s_sleep 0
	s_cbranch_scc1 .LBB0_1863
	v_readlane_b32 s0, v255, 22
	v_readlane_b32 s1, v255, 23
	s_nop 4
	global_load_dword v2, v0, s[0:1] sc1
	s_waitcnt vmcnt(0)
	v_cmp_eq_u32_e32 vcc, 0, v2
	s_cbranch_vccnz .LBB0_1865
	s_mov_b64 s[52:53], 0
	s_mov_b64 s[50:51], -1

; __device__ __forceinline__ unsigned xb_ld(unsigned* p)              { return __hip_atomic_load(p, __ATOMIC_RELAXED, __HIP_MEMORY_SCOPE_AGENT); }
; __device__ __forceinline__ void xcd_barrier_complete(unsigned* bar, unsigned x, unsigned& nloc, unsigned& nx) {
;     ...
;     for (;;) {
;         sum = 0u; cnt = 0u; mine = 0u;
; #pragma unroll
;         for (unsigned j = 0; j < 16; ++j) { const unsigned c = xb_ld(&bar[XB_XCNT(j)]); sum += c; cnt += (c > 0u) ? 1u : 0u; mine = (j == x) ? c : mine; }
;         if (sum == G) break;
;         __builtin_amdgcn_s_sleep(1);
;         if ((++sp & 255u) == 0u) { if (xb_ld(&bar[XB_TMO])) break; if (sp > XB_SPIN_CAP) { atomicAdd(&bar[XB_TMO], 1u); break; } }
;     }
.LBB0_1916:
	global_load_dword v12, v0, s[34:35] offset:1024 sc1
	global_load_dword v1, v0, s[34:35] offset:1280 sc1
	s_waitcnt lgkmcnt(0)
	global_load_dword v2, v0, s[34:35] offset:1536 sc1
	global_load_dword v3, v0, s[34:35] offset:1792 sc1
	global_load_dword v4, v0, s[34:35] offset:2048 sc1
	global_load_dword v5, v0, s[34:35] offset:2304 sc1
	global_load_dword v6, v0, s[34:35] offset:2560 sc1
	global_load_dword v7, v0, s[34:35] offset:2816 sc1
	global_load_dword v8, v0, s[34:35] offset:3072 sc1
	global_load_dword v9, v0, s[34:35] offset:3328 sc1
	global_load_dword v10, v0, s[34:35] offset:3584 sc1
	global_load_dword v11, v0, s[34:35] offset:3840 sc1
	v_readlane_b32 s0, v254, 60
	v_readlane_b32 s1, v254, 61
	s_nop 4
	global_load_dword v13, v0, s[0:1] sc1
	global_load_dword v14, v0, s[78:79] sc1
	global_load_dword v15, v0, s[80:81] sc1
	global_load_dword v16, v0, s[76:77] sc1
	s_mov_b64 s[12:13], -1
	s_mov_b64 s[14:15], -1
	s_waitcnt vmcnt(14)
	v_add_u32_e32 v17, v1, v12
	s_waitcnt vmcnt(13)
	v_add_u32_e32 v17, v17, v2
	s_waitcnt vmcnt(12)
	v_add_u32_e32 v17, v17, v3
	s_waitcnt vmcnt(11)
	v_add_u32_e32 v17, v17, v4
	s_waitcnt vmcnt(10)
	v_add_u32_e32 v17, v17, v5
	s_waitcnt vmcnt(9)
	v_add_u32_e32 v17, v17, v6
	s_waitcnt vmcnt(8)
	v_add_u32_e32 v17, v17, v7
	s_waitcnt vmcnt(7)
	v_add_u32_e32 v17, v17, v8
	s_waitcnt vmcnt(6)
	v_add_u32_e32 v17, v17, v9
	s_waitcnt vmcnt(5)
	v_add_u32_e32 v17, v17, v10
	s_waitcnt vmcnt(4)
	v_add_u32_e32 v17, v17, v11
	s_waitcnt vmcnt(3)
	v_add_u32_e32 v17, v17, v13
	s_waitcnt vmcnt(2)
	v_add_u32_e32 v17, v17, v14
	s_waitcnt vmcnt(1)
	v_add_u32_e32 v17, v17, v15
	s_waitcnt vmcnt(0)
	v_add_u32_e32 v17, v17, v16
	v_cmp_eq_u32_e32 vcc, s36, v17
	s_cbranch_vccnz .LBB0_1915
	s_and_b32 s0, s4, 0xff
	s_cmp_eq_u32 s0, 0
	s_mov_b64 s[40:41], -1
	s_sleep 0
	s_cbranch_scc0 .LBB0_1920
	global_load_dword v17, v0, s[18:19] sc1
	s_waitcnt vmcnt(0)
	v_cmp_eq_u32_e32 vcc, 0, v17
	s_cbranch_vccnz .LBB0_1922
	s_mov_b64 s[40:41], 0

.LBB0_1935:
	s_and_b32 s0, s4, 0xff
	s_mov_b64 s[46:47], -1
	s_cmp_lg_u32 s0, 0
	s_mov_b64 s[50:51], -1
	s_sleep 0
	s_cbranch_scc1 .LBB0_1938
	global_load_dword v2, v0, s[18:19] sc1
	s_waitcnt vmcnt(0)
	v_cmp_eq_u32_e32 vcc, 0, v2
	s_cbranch_vccnz .LBB0_1940
	s_mov_b64 s[50:51], 0
	s_mov_b64 s[48:49], -1

.LBB0_1974:
	s_sleep 0
	global_load_dword v2, v0, s[12:13] offset:32 sc1
	s_waitcnt vmcnt(0)
	v_and_b32_e32 v2, 0xffff0000, v2
	v_cmp_ne_u32_e32 vcc, v2, v1
	s_or_b64 s[14:15], vcc, s[14:15]
	s_andn2_b64 exec, exec, s[14:15]
	s_cbranch_execnz .LBB0_1974
	s_getpc_b64 s[98:99]
